# speedup vs baseline: 1.0040x; 1.0014x over previous
.Lpost_go:
	v_lshlrev_b32_e32 v2, 16, v35
	v_mul_f32_e32 v1, 0xbfb8aa3b, v2
	v_exp_f32_e32 v1, v1
	v_lshlrev_b32_e32 v56, 16, v34
	v_lshlrev_b32_e32 v3, 16, v31
	v_and_b32_e32 v47, 0xffff0000, v31
	v_add_f32_e32 v1, 1.0, v1
	v_rcp_f32_e32 v48, v1
	v_mul_f32_e32 v1, 0xbfb8aa3b, v56
	v_exp_f32_e32 v1, v1
	v_lshlrev_b32_e32 v57, 16, v30
	v_and_b32_e32 v31, 0xffff0000, v30
	v_and_b32_e32 v30, 0xffff0000, v34
	v_add_f32_e32 v1, 1.0, v1
	v_rcp_f32_e32 v58, v1
	v_mul_f32_e32 v1, 0xbfb8aa3b, v30
	v_lshlrev_b32_e32 v60, 16, v33
	v_exp_f32_e32 v1, v1
	v_mul_f32_e32 v37, 0xbfb8aa3b, v60
	v_exp_f32_e32 v37, v37
	v_and_b32_e32 v66, 0xffff0000, v33
	v_add_f32_e32 v1, 1.0, v1
	v_rcp_f32_e32 v62, v1
	v_add_f32_e32 v1, 1.0, v37
	v_rcp_f32_e32 v64, v1
	v_mul_f32_e32 v1, 0xbfb8aa3b, v66
	v_exp_f32_e32 v1, v1
	v_lshlrev_b32_e32 v72, 16, v32
	v_and_b32_e32 v32, 0xffff0000, v32
	v_lshlrev_b32_e32 v61, 16, v29
	v_add_f32_e32 v1, 1.0, v1
	v_rcp_f32_e32 v70, v1
	v_mul_f32_e32 v1, 0xbfb8aa3b, v72
	v_and_b32_e32 v67, 0xffff0000, v29
	v_exp_f32_e32 v1, v1
	v_mul_f32_e32 v29, 0xbfb8aa3b, v32
	v_exp_f32_e32 v29, v29
	v_lshlrev_b32_e32 v76, 16, v23
	v_add_f32_e32 v1, 1.0, v1
	v_rcp_f32_e32 v74, v1
	v_add_f32_e32 v1, 1.0, v29
	v_lshlrev_b32_e32 v73, 16, v28
	v_and_b32_e32 v33, 0xffff0000, v28
	v_rcp_f32_e32 v28, v1
	v_mul_f32_e32 v1, 0xbfb8aa3b, v76
	v_and_b32_e32 v78, 0xffff0000, v23
	v_exp_f32_e32 v1, v1
	v_mul_f32_e32 v23, 0xbfb8aa3b, v78
	v_exp_f32_e32 v23, v23
	v_lshlrev_b32_e32 v84, 16, v22
	v_add_f32_e32 v1, 1.0, v1
	v_rcp_f32_e32 v80, v1
	v_add_f32_e32 v1, 1.0, v23
	v_rcp_f32_e32 v82, v1
	v_mul_f32_e32 v1, 0xbfb8aa3b, v84
	v_and_b32_e32 v22, 0xffff0000, v22
	v_exp_f32_e32 v1, v1
	v_mul_f32_e32 v23, 0xbfb8aa3b, v22
	v_lshlrev_b32_e32 v77, 16, v27
	v_and_b32_e32 v79, 0xffff0000, v27
	v_exp_f32_e32 v27, v23
	v_lshlrev_b32_e32 v89, 16, v24
	v_add_f32_e32 v1, 1.0, v1
	v_and_b32_e32 v91, 0xffff0000, v24
	v_mul_f32_e32 v24, v89, v89
	v_rcp_f32_e32 v86, v1
	v_add_f32_e32 v1, 1.0, v27
	v_lshlrev_b32_e32 v27, 16, v25
	v_fmac_f32_e32 v24, v91, v91
	v_and_b32_e32 v25, 0xffff0000, v25
	v_fmac_f32_e32 v24, v27, v27
	v_lshlrev_b32_e32 v85, 16, v26
	v_fmac_f32_e32 v24, v25, v25
	v_and_b32_e32 v23, 0xffff0000, v26
	v_fmac_f32_e32 v24, v85, v85
	v_fmac_f32_e32 v24, v23, v23
	v_fmac_f32_e32 v24, v77, v77
	v_fmac_f32_e32 v24, v79, v79
	v_mov_b32_e32 v68, v67
	v_mov_b32_e32 v69, v61
	v_fmac_f32_e32 v24, v73, v73
	v_pk_mul_f32 v[68:69], v[68:69], v[68:69]
	v_fmac_f32_e32 v24, v33, v33
	v_and_b32_e32 v46, 0xffff0000, v35
	v_mov_b32_e32 v34, v31
	v_mov_b32_e32 v35, v57
	v_add_f32_e32 v24, v69, v24
	v_pk_mul_f32 v[34:35], v[34:35], v[34:35]
	v_add_f32_e32 v24, v68, v24
	v_mov_b32_e32 v54, v47
	v_mov_b32_e32 v55, v3
	v_add_f32_e32 v24, v35, v24
	v_pk_mul_f32 v[54:55], v[54:55], v[54:55]
	v_add_f32_e32 v24, v34, v24
	v_add_f32_e32 v24, v55, v24
	v_add_f32_e32 v34, v54, v24
	ds_bpermute_b32 v35, v41, v34
	v_lshlrev_b32_e32 v26, 16, v21
	v_mul_f32_e32 v29, 0xbfb8aa3b, v26
	v_and_b32_e32 v24, 0xffff0000, v21
	v_exp_f32_e32 v29, v29
	s_waitcnt lgkmcnt(0)
	v_add_f32_e32 v35, v34, v35
	v_mul_f32_e32 v21, 0xbfb8aa3b, v24
	ds_bpermute_b32 v37, v50, v35
	v_exp_f32_e32 v21, v21
	v_rcp_f32_e32 v34, v1
	v_add_f32_e32 v1, 1.0, v29
	v_rcp_f32_e32 v54, v1
	v_add_f32_e32 v1, 1.0, v21
	s_waitcnt lgkmcnt(0)
	v_add_f32_e32 v21, v35, v37
	ds_bpermute_b32 v29, v51, v21
	v_rcp_f32_e32 v68, v1
	v_lshlrev_b32_e32 v88, 16, v20
	v_mul_f32_e32 v35, 0xbfb8aa3b, v88
	v_exp_f32_e32 v35, v35
	s_waitcnt lgkmcnt(0)
	v_add_f32_e32 v1, v21, v29
	ds_bpermute_b32 v21, v52, v1
	v_and_b32_e32 v90, 0xffff0000, v20
	v_mul_f32_e32 v20, 0xbfb8aa3b, v90
	s_and_b64 s[4:5], exec, vcc
	v_add_f32_e32 v29, 1.0, v35
	s_waitcnt lgkmcnt(0)
	v_add_f32_e32 v1, v1, v21
	v_fmamk_f32 v1, v1, 0x3b800000, v208
	v_exp_f32_e32 v35, v20
	v_mul_f32_e32 v20, 0x4b800000, v1
	v_cmp_gt_f32_e32 vcc, s95, v1
	s_or_b64 s[12:13], s[4:5], s[12:13]
	v_add_f32_e32 v21, 1.0, v35
	v_cndmask_b32_e32 v1, v1, v20, vcc
	v_rsq_f32_e32 v1, v1
	v_rcp_f32_e32 v20, v29
	v_rcp_f32_e32 v92, v21
	v_readlane_b32 s0, v254, 51
	v_mul_f32_e32 v21, 0x45800000, v1
	v_cndmask_b32_e32 v21, v1, v21, vcc
	v_pk_mul_f32 v[88:89], v[20:21], v[88:89]
	v_mov_b32_e32 v55, v21
	v_mov_b32_e32 v69, v21
	v_mul_f32_e32 v20, 0xbfb8aa3b, v46
	v_pk_mul_f32 v[26:27], v[54:55], v[26:27]
	v_pk_mul_f32 v[24:25], v[68:69], v[24:25]
	v_mov_b32_e32 v87, v21
	v_mov_b32_e32 v35, v21
	v_exp_f32_e32 v20, v20
	v_mul_f32_e32 v26, v26, v27
	v_mul_f32_e32 v27, v24, v25
	v_pk_mul_f32 v[24:25], v[86:87], v[84:85]
	v_pk_mul_f32 v[22:23], v[34:35], v[22:23]
	v_mov_b32_e32 v81, v21
	v_mul_f32_e32 v24, v24, v25
	v_mul_f32_e32 v25, v22, v23
	v_pk_mul_f32 v[22:23], v[80:81], v[76:77]
	v_mov_b32_e32 v83, v21
	v_mul_f32_e32 v34, v22, v23
	v_pk_mul_f32 v[22:23], v[82:83], v[78:79]
	v_mov_b32_e32 v75, v21
	v_mul_f32_e32 v35, v22, v23
	v_pk_mul_f32 v[22:23], v[74:75], v[72:73]
	v_mov_b32_e32 v29, v21
	v_add_f32_e32 v20, 1.0, v20
	v_mul_f32_e32 v53, v22, v23
	v_pk_mul_f32 v[22:23], v[28:29], v[32:33]
	v_mov_b32_e32 v65, v21
	v_rcp_f32_e32 v20, v20
	v_mul_f32_e32 v28, v22, v23
	v_pk_mul_f32 v[22:23], v[64:65], v[60:61]
	v_mov_b32_e32 v71, v21
	v_mul_f32_e32 v29, v22, v23
	v_pk_mul_f32 v[22:23], v[70:71], v[66:67]
	v_mov_b32_e32 v59, v21
	v_mov_b32_e32 v49, v21
	v_mov_b32_e32 v93, v21
	v_mul_f32_e32 v32, v22, v23
	v_pk_mul_f32 v[22:23], v[58:59], v[56:57]
	v_mov_b32_e32 v63, v21
	v_pk_mul_f32 v[2:3], v[48:49], v[2:3]
	v_mul_f32_e32 v1, v88, v89
	v_pk_mul_f32 v[88:89], v[92:93], v[90:91]
	v_mul_f32_e32 v33, v22, v23
	v_pk_mul_f32 v[22:23], v[62:63], v[30:31]
	v_mul_f32_e32 v31, v2, v3
	v_pk_mul_f32 v[2:3], v[20:21], v[46:47]
	v_mul_f32_e32 v37, v88, v89
	v_mul_f32_e32 v30, v22, v23
	v_mul_f32_e32 v46, v2, v3
	v_lshl_add_u64 v[2:3], v[42:43], 1, s[6:7]
	v_cvt_pk_bf16_f32 v20, v1, v37
	v_cvt_pk_bf16_f32 v21, v26, v27
	v_cvt_pk_bf16_f32 v22, v24, v25
	v_cvt_pk_bf16_f32 v23, v34, v35
	v_cvt_pk_bf16_f32 v24, v53, v28
	v_cvt_pk_bf16_f32 v25, v29, v32
	v_cvt_pk_bf16_f32 v26, v33, v30
	v_cvt_pk_bf16_f32 v27, v31, v46
	v_readlane_b32 s4, v254, 37
	global_store_dwordx4 v[2:3], v[20:23], off
	global_store_dwordx4 v[2:3], v[24:27], off offset:16
	s_waitcnt vmcnt(2)
	v_readlane_b32 s1, v254, 52
	v_readlane_b32 s5, v254, 38
	v_mov_b64_e32 v[26:27], v[10:11]
	v_mov_b64_e32 v[30:31], v[6:7]
	v_mov_b64_e32 v[22:23], v[18:19]
	v_mov_b64_e32 v[34:35], v[14:15]
	v_lshl_add_u64 v[42:43], v[42:43], 0, s[0:1]
	v_lshl_add_u64 v[44:45], v[44:45], 0, s[4:5]
	v_mov_b64_e32 v[24:25], v[8:9]
	v_mov_b64_e32 v[28:29], v[4:5]
	v_mov_b64_e32 v[20:21], v[16:17]
	v_mov_b64_e32 v[32:33], v[12:13]
	s_andn2_b64 exec, exec, s[12:13]
	s_cbranch_execz .LBB0_103
.LBB0_96:
	v_mov_b32_e32 v2, v0
	v_mov_b32_e32 v3, v0
	v_add_u32_e32 v36, s98, v36
	v_mov_b32_e32 v1, v0
	v_mov_b64_e32 v[14:15], v[2:3]
	v_mov_b64_e32 v[18:19], v[2:3]
	v_mov_b64_e32 v[6:7], v[2:3]
	v_mov_b64_e32 v[10:11], v[2:3]
	v_cmp_gt_i32_e64 s[4:5], s91, v36
	v_cmp_lt_i32_e32 vcc, s93, v36
	v_mov_b64_e32 v[12:13], v[0:1]
	v_mov_b64_e32 v[16:17], v[0:1]
	v_mov_b64_e32 v[4:5], v[0:1]
	v_mov_b64_e32 v[8:9], v[0:1]
	s_and_saveexec_b64 s[14:15], s[4:5]
	s_cbranch_execz .LBB0_95
	v_ashrrev_i32_e32 v1, 10, v36
	v_and_or_b32 v4, v1, -4, v39
	v_ashrrev_i32_e32 v5, 31, v4
	v_lshlrev_b64 v[4:5], 15, v[4:5]
	s_movk_i32 s4, 0xfff
	v_and_or_b32 v1, v36, s4, v4
	v_or_b32_e32 v4, v1, v40
	v_lshlrev_b64 v[4:5], 6, v[4:5]
	v_lshl_or_b32 v4, v38, 1, v4
	v_lshl_add_u64 v[8:9], s[8:9], 0, v[4:5]
	v_lshl_add_u64 v[2:3], v[44:45], 1, s[10:11]
	global_load_dwordx4 v[4:7], v[8:9], off offset:16
	s_nop 0
	global_load_dwordx4 v[8:11], v[8:9], off
	s_nop 0
	global_load_dwordx4 v[12:15], v[2:3], off offset:16
	global_load_dwordx4 v[16:19], v[2:3], off
	s_or_b64 exec, exec, s[14:15]
	s_waitcnt vmcnt(4)
	s_branch .Lpost_go
